# P0 transposes: whole item (32+32 loads) in one pass
# baseline (speedup 1.0000x reference)
; __global__ void __launch_bounds__(512, 2) fwd_mega(Params P) {
;     ...
;                 const int kb = it / nrb, rb = it % nrb, k0 = kb * 64, r0 = rb * 32, dr = r0 + (lane & 31);
;                 int c = dr;
;                 if (mapid == 1) c = MapIn{}(dr); else if (mapid == 2) c = MapUq{}(dr);
;                 else if (mapid == 3) { const int e = dr & 7; c = 4 * (dr >> 3) + (e & 3); if (e >= 4) W = pp->in[25]; }
; #pragma unroll 16
;                 for (int i = 0; i < 32; ++i) { const int kk = 2 * i + (lane >> 5); float v = c >= 0 ? W[(size_t)(k0 + kk) * ldw + c] : 0.f; if (gk) v *= gk[k0 + kk]; scr[kk * 33 + (lane & 31)] = v; }
.LBB0_60:
	s_branch .LBB0_7
.LBB0_61:
	v_mov_b32_e32 v80, 0
	v_mov_b32_e32 v81, 0
	v_mov_b32_e32 v82, 0
	v_mov_b32_e32 v83, 0
	v_mov_b32_e32 v84, 0
	v_mov_b32_e32 v85, 0
	v_mov_b32_e32 v86, 0
	v_mov_b32_e32 v87, 0
	v_mov_b32_e32 v88, 0
	v_mov_b32_e32 v89, 0
	v_mov_b32_e32 v90, 0
	v_mov_b32_e32 v91, 0
	v_mov_b32_e32 v92, 0
	v_mov_b32_e32 v93, 0
	v_mov_b32_e32 v94, 0
	v_mov_b32_e32 v95, 0
	v_mov_b32_e32 v96, 0
	v_mov_b32_e32 v97, 0
	v_mov_b32_e32 v98, 0
	v_mov_b32_e32 v99, 0
	v_mov_b32_e32 v100, 0
	v_mov_b32_e32 v101, 0
	v_mov_b32_e32 v102, 0
	v_mov_b32_e32 v103, 0
	v_mov_b32_e32 v104, 0
	v_mov_b32_e32 v105, 0
	v_mov_b32_e32 v106, 0
	v_mov_b32_e32 v107, 0
	v_mov_b32_e32 v108, 0
	v_mov_b32_e32 v109, 0
	v_mov_b32_e32 v110, 0
	v_mov_b32_e32 v111, 0
	v_cndmask_b32_e64 v21, 0, 1, s[36:37]
	v_cmp_ne_u32_e64 s[10:11], 1, v21
	s_and_saveexec_b64 s[38:39], s[8:9]
	s_cbranch_execz .Lmy_tr_noload
	v_mov_b32_e32 v12, v4
	v_ashrrev_i32_e32 v13, 31, v12
	v_mul_lo_u32 v20, s34, v13
	v_mul_lo_u32 v21, s35, v12
	v_mad_u64_u32 v[12:13], s[56:57], s34, v12, 0
	v_add3_u32 v13, v13, v20, v21
	v_lshl_add_u64 v[12:13], v[12:13], 2, v[8:9]
	global_load_dword v80, v[12:13], off
	v_add_u32_e32 v12, 2, v4
	v_ashrrev_i32_e32 v13, 31, v12
	v_mul_lo_u32 v20, s34, v13
	v_mul_lo_u32 v21, s35, v12
	v_mad_u64_u32 v[12:13], s[56:57], s34, v12, 0
	v_add3_u32 v13, v13, v20, v21
	v_lshl_add_u64 v[12:13], v[12:13], 2, v[8:9]
	global_load_dword v81, v[12:13], off
	v_add_u32_e32 v12, 4, v4
	v_ashrrev_i32_e32 v13, 31, v12
	v_mul_lo_u32 v20, s34, v13
	v_mul_lo_u32 v21, s35, v12
	v_mad_u64_u32 v[12:13], s[56:57], s34, v12, 0
	v_add3_u32 v13, v13, v20, v21
	v_lshl_add_u64 v[12:13], v[12:13], 2, v[8:9]
	global_load_dword v82, v[12:13], off
	v_add_u32_e32 v12, 6, v4
	v_ashrrev_i32_e32 v13, 31, v12
	v_mul_lo_u32 v20, s34, v13
	v_mul_lo_u32 v21, s35, v12
	v_mad_u64_u32 v[12:13], s[56:57], s34, v12, 0
	v_add3_u32 v13, v13, v20, v21
	v_lshl_add_u64 v[12:13], v[12:13], 2, v[8:9]
	global_load_dword v83, v[12:13], off
	v_add_u32_e32 v12, 8, v4
	v_ashrrev_i32_e32 v13, 31, v12
	v_mul_lo_u32 v20, s34, v13
	v_mul_lo_u32 v21, s35, v12
	v_mad_u64_u32 v[12:13], s[56:57], s34, v12, 0
	v_add3_u32 v13, v13, v20, v21
	v_lshl_add_u64 v[12:13], v[12:13], 2, v[8:9]
	global_load_dword v84, v[12:13], off
	v_add_u32_e32 v12, 10, v4
	v_ashrrev_i32_e32 v13, 31, v12
	v_mul_lo_u32 v20, s34, v13
	v_mul_lo_u32 v21, s35, v12
	v_mad_u64_u32 v[12:13], s[56:57], s34, v12, 0
	v_add3_u32 v13, v13, v20, v21
	v_lshl_add_u64 v[12:13], v[12:13], 2, v[8:9]
	global_load_dword v85, v[12:13], off
	v_add_u32_e32 v12, 12, v4
	v_ashrrev_i32_e32 v13, 31, v12
	v_mul_lo_u32 v20, s34, v13
	v_mul_lo_u32 v21, s35, v12
	v_mad_u64_u32 v[12:13], s[56:57], s34, v12, 0
	v_add3_u32 v13, v13, v20, v21
	v_lshl_add_u64 v[12:13], v[12:13], 2, v[8:9]
	global_load_dword v86, v[12:13], off
	v_add_u32_e32 v12, 14, v4
	v_ashrrev_i32_e32 v13, 31, v12
	v_mul_lo_u32 v20, s34, v13
	v_mul_lo_u32 v21, s35, v12
	v_mad_u64_u32 v[12:13], s[56:57], s34, v12, 0
	v_add3_u32 v13, v13, v20, v21
	v_lshl_add_u64 v[12:13], v[12:13], 2, v[8:9]
	global_load_dword v87, v[12:13], off
	v_add_u32_e32 v12, 16, v4
	v_ashrrev_i32_e32 v13, 31, v12
	v_mul_lo_u32 v20, s34, v13
	v_mul_lo_u32 v21, s35, v12
	v_mad_u64_u32 v[12:13], s[56:57], s34, v12, 0
	v_add3_u32 v13, v13, v20, v21
	v_lshl_add_u64 v[12:13], v[12:13], 2, v[8:9]
	global_load_dword v88, v[12:13], off
	v_add_u32_e32 v12, 18, v4
	v_ashrrev_i32_e32 v13, 31, v12
	v_mul_lo_u32 v20, s34, v13
	v_mul_lo_u32 v21, s35, v12
	v_mad_u64_u32 v[12:13], s[56:57], s34, v12, 0
	v_add3_u32 v13, v13, v20, v21
	v_lshl_add_u64 v[12:13], v[12:13], 2, v[8:9]
	global_load_dword v89, v[12:13], off
	v_add_u32_e32 v12, 20, v4
	v_ashrrev_i32_e32 v13, 31, v12
	v_mul_lo_u32 v20, s34, v13
	v_mul_lo_u32 v21, s35, v12
	v_mad_u64_u32 v[12:13], s[56:57], s34, v12, 0
	v_add3_u32 v13, v13, v20, v21
	v_lshl_add_u64 v[12:13], v[12:13], 2, v[8:9]
	global_load_dword v90, v[12:13], off
	v_add_u32_e32 v12, 22, v4
	v_ashrrev_i32_e32 v13, 31, v12
	v_mul_lo_u32 v20, s34, v13
	v_mul_lo_u32 v21, s35, v12
	v_mad_u64_u32 v[12:13], s[56:57], s34, v12, 0
	v_add3_u32 v13, v13, v20, v21
	v_lshl_add_u64 v[12:13], v[12:13], 2, v[8:9]
	global_load_dword v91, v[12:13], off
	v_add_u32_e32 v12, 24, v4
	v_ashrrev_i32_e32 v13, 31, v12
	v_mul_lo_u32 v20, s34, v13
	v_mul_lo_u32 v21, s35, v12
	v_mad_u64_u32 v[12:13], s[56:57], s34, v12, 0
	v_add3_u32 v13, v13, v20, v21
	v_lshl_add_u64 v[12:13], v[12:13], 2, v[8:9]
	global_load_dword v92, v[12:13], off
	v_add_u32_e32 v12, 26, v4
	v_ashrrev_i32_e32 v13, 31, v12
	v_mul_lo_u32 v20, s34, v13
	v_mul_lo_u32 v21, s35, v12
	v_mad_u64_u32 v[12:13], s[56:57], s34, v12, 0
	v_add3_u32 v13, v13, v20, v21
	v_lshl_add_u64 v[12:13], v[12:13], 2, v[8:9]
	global_load_dword v93, v[12:13], off
	v_add_u32_e32 v12, 28, v4
	v_ashrrev_i32_e32 v13, 31, v12
	v_mul_lo_u32 v20, s34, v13
	v_mul_lo_u32 v21, s35, v12
	v_mad_u64_u32 v[12:13], s[56:57], s34, v12, 0
	v_add3_u32 v13, v13, v20, v21
	v_lshl_add_u64 v[12:13], v[12:13], 2, v[8:9]
	global_load_dword v94, v[12:13], off
	v_add_u32_e32 v12, 30, v4
	v_ashrrev_i32_e32 v13, 31, v12
	v_mul_lo_u32 v20, s34, v13
	v_mul_lo_u32 v21, s35, v12
	v_mad_u64_u32 v[12:13], s[56:57], s34, v12, 0
	v_add3_u32 v13, v13, v20, v21
	v_lshl_add_u64 v[12:13], v[12:13], 2, v[8:9]
	global_load_dword v95, v[12:13], off
	v_add_u32_e32 v12, 32, v4
	v_ashrrev_i32_e32 v13, 31, v12
	v_mul_lo_u32 v20, s34, v13
	v_mul_lo_u32 v21, s35, v12
	v_mad_u64_u32 v[12:13], s[56:57], s34, v12, 0
	v_add3_u32 v13, v13, v20, v21
	v_lshl_add_u64 v[12:13], v[12:13], 2, v[8:9]
	global_load_dword v96, v[12:13], off
	v_add_u32_e32 v12, 34, v4
; __global__ void __launch_bounds__(512, 2) fwd_mega(Params P) {
;     ...
; #pragma unroll 16
;                 for (int i = 0; i < 32; ++i) { const int kk = 2 * i + (lane >> 5); float v = c >= 0 ? W[(size_t)(k0 + kk) * ldw + c] : 0.f; if (gk) v *= gk[k0 + kk]; scr[kk * 33 + (lane & 31)] = v; }
	v_ashrrev_i32_e32 v13, 31, v12
	v_mul_lo_u32 v20, s34, v13
	v_mul_lo_u32 v21, s35, v12
	v_mad_u64_u32 v[12:13], s[56:57], s34, v12, 0
	v_add3_u32 v13, v13, v20, v21
	v_lshl_add_u64 v[12:13], v[12:13], 2, v[8:9]
	global_load_dword v97, v[12:13], off
	v_add_u32_e32 v12, 36, v4
	v_ashrrev_i32_e32 v13, 31, v12
	v_mul_lo_u32 v20, s34, v13
	v_mul_lo_u32 v21, s35, v12
	v_mad_u64_u32 v[12:13], s[56:57], s34, v12, 0
	v_add3_u32 v13, v13, v20, v21
	v_lshl_add_u64 v[12:13], v[12:13], 2, v[8:9]
	global_load_dword v98, v[12:13], off
	v_add_u32_e32 v12, 38, v4
	v_ashrrev_i32_e32 v13, 31, v12
	v_mul_lo_u32 v20, s34, v13
	v_mul_lo_u32 v21, s35, v12
	v_mad_u64_u32 v[12:13], s[56:57], s34, v12, 0
	v_add3_u32 v13, v13, v20, v21
	v_lshl_add_u64 v[12:13], v[12:13], 2, v[8:9]
	global_load_dword v99, v[12:13], off
	v_add_u32_e32 v12, 40, v4
	v_ashrrev_i32_e32 v13, 31, v12
	v_mul_lo_u32 v20, s34, v13
	v_mul_lo_u32 v21, s35, v12
	v_mad_u64_u32 v[12:13], s[56:57], s34, v12, 0
	v_add3_u32 v13, v13, v20, v21
	v_lshl_add_u64 v[12:13], v[12:13], 2, v[8:9]
	global_load_dword v100, v[12:13], off
	v_add_u32_e32 v12, 42, v4
	v_ashrrev_i32_e32 v13, 31, v12
	v_mul_lo_u32 v20, s34, v13
	v_mul_lo_u32 v21, s35, v12
	v_mad_u64_u32 v[12:13], s[56:57], s34, v12, 0
	v_add3_u32 v13, v13, v20, v21
	v_lshl_add_u64 v[12:13], v[12:13], 2, v[8:9]
	global_load_dword v101, v[12:13], off
	v_add_u32_e32 v12, 44, v4
	v_ashrrev_i32_e32 v13, 31, v12
	v_mul_lo_u32 v20, s34, v13
	v_mul_lo_u32 v21, s35, v12
	v_mad_u64_u32 v[12:13], s[56:57], s34, v12, 0
	v_add3_u32 v13, v13, v20, v21
	v_lshl_add_u64 v[12:13], v[12:13], 2, v[8:9]
	global_load_dword v102, v[12:13], off
	v_add_u32_e32 v12, 46, v4
	v_ashrrev_i32_e32 v13, 31, v12
	v_mul_lo_u32 v20, s34, v13
	v_mul_lo_u32 v21, s35, v12
	v_mad_u64_u32 v[12:13], s[56:57], s34, v12, 0
	v_add3_u32 v13, v13, v20, v21
	v_lshl_add_u64 v[12:13], v[12:13], 2, v[8:9]
	global_load_dword v103, v[12:13], off
	v_add_u32_e32 v12, 48, v4
	v_ashrrev_i32_e32 v13, 31, v12
	v_mul_lo_u32 v20, s34, v13
	v_mul_lo_u32 v21, s35, v12
	v_mad_u64_u32 v[12:13], s[56:57], s34, v12, 0
	v_add3_u32 v13, v13, v20, v21
	v_lshl_add_u64 v[12:13], v[12:13], 2, v[8:9]
	global_load_dword v104, v[12:13], off
	v_add_u32_e32 v12, 50, v4
	v_ashrrev_i32_e32 v13, 31, v12
	v_mul_lo_u32 v20, s34, v13
	v_mul_lo_u32 v21, s35, v12
	v_mad_u64_u32 v[12:13], s[56:57], s34, v12, 0
	v_add3_u32 v13, v13, v20, v21
	v_lshl_add_u64 v[12:13], v[12:13], 2, v[8:9]
	global_load_dword v105, v[12:13], off
	v_add_u32_e32 v12, 52, v4
	v_ashrrev_i32_e32 v13, 31, v12
	v_mul_lo_u32 v20, s34, v13
	v_mul_lo_u32 v21, s35, v12
	v_mad_u64_u32 v[12:13], s[56:57], s34, v12, 0
	v_add3_u32 v13, v13, v20, v21
	v_lshl_add_u64 v[12:13], v[12:13], 2, v[8:9]
	global_load_dword v106, v[12:13], off
	v_add_u32_e32 v12, 54, v4
	v_ashrrev_i32_e32 v13, 31, v12
	v_mul_lo_u32 v20, s34, v13
	v_mul_lo_u32 v21, s35, v12
	v_mad_u64_u32 v[12:13], s[56:57], s34, v12, 0
	v_add3_u32 v13, v13, v20, v21
	v_lshl_add_u64 v[12:13], v[12:13], 2, v[8:9]
	global_load_dword v107, v[12:13], off
	v_add_u32_e32 v12, 56, v4
	v_ashrrev_i32_e32 v13, 31, v12
	v_mul_lo_u32 v20, s34, v13
	v_mul_lo_u32 v21, s35, v12
	v_mad_u64_u32 v[12:13], s[56:57], s34, v12, 0
	v_add3_u32 v13, v13, v20, v21
	v_lshl_add_u64 v[12:13], v[12:13], 2, v[8:9]
	global_load_dword v108, v[12:13], off
	v_add_u32_e32 v12, 58, v4
	v_ashrrev_i32_e32 v13, 31, v12
	v_mul_lo_u32 v20, s34, v13
	v_mul_lo_u32 v21, s35, v12
	v_mad_u64_u32 v[12:13], s[56:57], s34, v12, 0
	v_add3_u32 v13, v13, v20, v21
	v_lshl_add_u64 v[12:13], v[12:13], 2, v[8:9]
	global_load_dword v109, v[12:13], off
	v_add_u32_e32 v12, 60, v4
	v_ashrrev_i32_e32 v13, 31, v12
	v_mul_lo_u32 v20, s34, v13
	v_mul_lo_u32 v21, s35, v12
	v_mad_u64_u32 v[12:13], s[56:57], s34, v12, 0
	v_add3_u32 v13, v13, v20, v21
	v_lshl_add_u64 v[12:13], v[12:13], 2, v[8:9]
	global_load_dword v110, v[12:13], off
	v_add_u32_e32 v12, 62, v4
	v_ashrrev_i32_e32 v13, 31, v12
	v_mul_lo_u32 v20, s34, v13
	v_mul_lo_u32 v21, s35, v12
	v_mad_u64_u32 v[12:13], s[56:57], s34, v12, 0
	v_add3_u32 v13, v13, v20, v21
	v_lshl_add_u64 v[12:13], v[12:13], 2, v[8:9]
	global_load_dword v111, v[12:13], off
; __global__ void __launch_bounds__(512, 2) fwd_mega(Params P) {
;     ...
; #pragma unroll 16
;                 for (int i = 0; i < 32; ++i) { const int kk = 2 * i + (lane >> 5); float v = c >= 0 ? W[(size_t)(k0 + kk) * ldw + c] : 0.f; if (gk) v *= gk[k0 + kk]; scr[kk * 33 + (lane & 31)] = v; }
;                 asm volatile("s_waitcnt lgkmcnt(0)" ::: "memory");
.Lmy_tr_noload:
	s_or_b64 exec, exec, s[38:39]
	s_andn2_b64 vcc, exec, s[36:37]
	s_cbranch_vccnz .Lmy_tr_nogk
	global_load_dword v112, v[10:11], off offset:-120
	global_load_dword v113, v[10:11], off offset:-112
	global_load_dword v114, v[10:11], off offset:-104
	global_load_dword v115, v[10:11], off offset:-96
	global_load_dword v116, v[10:11], off offset:-88
	global_load_dword v117, v[10:11], off offset:-80
	global_load_dword v118, v[10:11], off offset:-72
	global_load_dword v119, v[10:11], off offset:-64
	global_load_dword v120, v[10:11], off offset:-56
	global_load_dword v121, v[10:11], off offset:-48
	global_load_dword v122, v[10:11], off offset:-40
	global_load_dword v123, v[10:11], off offset:-32
	global_load_dword v124, v[10:11], off offset:-24
	global_load_dword v125, v[10:11], off offset:-16
	global_load_dword v126, v[10:11], off offset:-8
	global_load_dword v127, v[10:11], off
	global_load_dword v128, v[10:11], off offset:8
	global_load_dword v129, v[10:11], off offset:16
	global_load_dword v130, v[10:11], off offset:24
	global_load_dword v131, v[10:11], off offset:32
	global_load_dword v132, v[10:11], off offset:40
	global_load_dword v133, v[10:11], off offset:48
	global_load_dword v134, v[10:11], off offset:56
	global_load_dword v135, v[10:11], off offset:64
	global_load_dword v136, v[10:11], off offset:72
	global_load_dword v137, v[10:11], off offset:80
	global_load_dword v138, v[10:11], off offset:88
	global_load_dword v139, v[10:11], off offset:96
	global_load_dword v140, v[10:11], off offset:104
	global_load_dword v141, v[10:11], off offset:112
	global_load_dword v142, v[10:11], off offset:120
	global_load_dword v143, v[10:11], off offset:128
	s_waitcnt vmcnt(31)
	v_mul_f32_e32 v80, v80, v112
	ds_write_b32 v7, v80
	s_waitcnt vmcnt(30)
	v_mul_f32_e32 v81, v81, v113
	ds_write_b32 v7, v81 offset:264
	s_waitcnt vmcnt(29)
	v_mul_f32_e32 v82, v82, v114
	ds_write_b32 v7, v82 offset:528
	s_waitcnt vmcnt(28)
	v_mul_f32_e32 v83, v83, v115
	ds_write_b32 v7, v83 offset:792
	s_waitcnt vmcnt(27)
	v_mul_f32_e32 v84, v84, v116
	ds_write_b32 v7, v84 offset:1056
	s_waitcnt vmcnt(26)
	v_mul_f32_e32 v85, v85, v117
	ds_write_b32 v7, v85 offset:1320
	s_waitcnt vmcnt(25)
	v_mul_f32_e32 v86, v86, v118
	ds_write_b32 v7, v86 offset:1584
	s_waitcnt vmcnt(24)
	v_mul_f32_e32 v87, v87, v119
	ds_write_b32 v7, v87 offset:1848
	s_waitcnt vmcnt(23)
	v_mul_f32_e32 v88, v88, v120
	ds_write_b32 v7, v88 offset:2112
	s_waitcnt vmcnt(22)
	v_mul_f32_e32 v89, v89, v121
	ds_write_b32 v7, v89 offset:2376
	s_waitcnt vmcnt(21)
	v_mul_f32_e32 v90, v90, v122
	ds_write_b32 v7, v90 offset:2640
	s_waitcnt vmcnt(20)
	v_mul_f32_e32 v91, v91, v123
	ds_write_b32 v7, v91 offset:2904
	s_waitcnt vmcnt(19)
	v_mul_f32_e32 v92, v92, v124
	ds_write_b32 v7, v92 offset:3168
	s_waitcnt vmcnt(18)
	v_mul_f32_e32 v93, v93, v125
	ds_write_b32 v7, v93 offset:3432
	s_waitcnt vmcnt(17)
	v_mul_f32_e32 v94, v94, v126
	ds_write_b32 v7, v94 offset:3696
	s_waitcnt vmcnt(16)
	v_mul_f32_e32 v95, v95, v127
	ds_write_b32 v7, v95 offset:3960
	s_waitcnt vmcnt(15)
	v_mul_f32_e32 v96, v96, v128
	ds_write_b32 v7, v96 offset:4224
	s_waitcnt vmcnt(14)
	v_mul_f32_e32 v97, v97, v129
	ds_write_b32 v7, v97 offset:4488
	s_waitcnt vmcnt(13)
	v_mul_f32_e32 v98, v98, v130
	ds_write_b32 v7, v98 offset:4752
	s_waitcnt vmcnt(12)
	v_mul_f32_e32 v99, v99, v131
	ds_write_b32 v7, v99 offset:5016
	s_waitcnt vmcnt(11)
	v_mul_f32_e32 v100, v100, v132
	ds_write_b32 v7, v100 offset:5280
	s_waitcnt vmcnt(10)
	v_mul_f32_e32 v101, v101, v133
	ds_write_b32 v7, v101 offset:5544
	s_waitcnt vmcnt(9)
	v_mul_f32_e32 v102, v102, v134
	ds_write_b32 v7, v102 offset:5808
	s_waitcnt vmcnt(8)
	v_mul_f32_e32 v103, v103, v135
	ds_write_b32 v7, v103 offset:6072
	s_waitcnt vmcnt(7)
	v_mul_f32_e32 v104, v104, v136
	ds_write_b32 v7, v104 offset:6336
	s_waitcnt vmcnt(6)
	v_mul_f32_e32 v105, v105, v137
	ds_write_b32 v7, v105 offset:6600
	s_waitcnt vmcnt(5)
	v_mul_f32_e32 v106, v106, v138
	ds_write_b32 v7, v106 offset:6864
	s_waitcnt vmcnt(4)
	v_mul_f32_e32 v107, v107, v139
	ds_write_b32 v7, v107 offset:7128
	s_waitcnt vmcnt(3)
	v_mul_f32_e32 v108, v108, v140
	ds_write_b32 v7, v108 offset:7392
	s_waitcnt vmcnt(2)
	v_mul_f32_e32 v109, v109, v141
	ds_write_b32 v7, v109 offset:7656
	s_waitcnt vmcnt(1)
	v_mul_f32_e32 v110, v110, v142
	ds_write_b32 v7, v110 offset:7920
	s_waitcnt vmcnt(0)
	v_mul_f32_e32 v111, v111, v143
	ds_write_b32 v7, v111 offset:8184
	s_branch .LBB0_7
.Lmy_tr_nogk:
	s_waitcnt vmcnt(31)
	ds_write_b32 v7, v80
	s_waitcnt vmcnt(30)
	ds_write_b32 v7, v81 offset:264
	s_waitcnt vmcnt(29)
	ds_write_b32 v7, v82 offset:528
	s_waitcnt vmcnt(28)
	ds_write_b32 v7, v83 offset:792
	s_waitcnt vmcnt(27)
	ds_write_b32 v7, v84 offset:1056
	s_waitcnt vmcnt(26)
	ds_write_b32 v7, v85 offset:1320
	s_waitcnt vmcnt(25)
	ds_write_b32 v7, v86 offset:1584
	s_waitcnt vmcnt(24)
	ds_write_b32 v7, v87 offset:1848
	s_waitcnt vmcnt(23)
	ds_write_b32 v7, v88 offset:2112
	s_waitcnt vmcnt(22)
	ds_write_b32 v7, v89 offset:2376
	s_waitcnt vmcnt(21)
	ds_write_b32 v7, v90 offset:2640
	s_waitcnt vmcnt(20)
	ds_write_b32 v7, v91 offset:2904
	s_waitcnt vmcnt(19)
	ds_write_b32 v7, v92 offset:3168
	s_waitcnt vmcnt(18)
	ds_write_b32 v7, v93 offset:3432
	s_waitcnt vmcnt(17)
	ds_write_b32 v7, v94 offset:3696
	s_waitcnt vmcnt(16)
	ds_write_b32 v7, v95 offset:3960
	s_waitcnt vmcnt(15)
	ds_write_b32 v7, v96 offset:4224
	s_waitcnt vmcnt(14)
	ds_write_b32 v7, v97 offset:4488
	s_waitcnt vmcnt(13)
	ds_write_b32 v7, v98 offset:4752
	s_waitcnt vmcnt(12)
	ds_write_b32 v7, v99 offset:5016
	s_waitcnt vmcnt(11)
	ds_write_b32 v7, v100 offset:5280
	s_waitcnt vmcnt(10)
	ds_write_b32 v7, v101 offset:5544
	s_waitcnt vmcnt(9)
	ds_write_b32 v7, v102 offset:5808
	s_waitcnt vmcnt(8)
	ds_write_b32 v7, v103 offset:6072
	s_waitcnt vmcnt(7)
	ds_write_b32 v7, v104 offset:6336
	s_waitcnt vmcnt(6)
	ds_write_b32 v7, v105 offset:6600
	s_waitcnt vmcnt(5)
	ds_write_b32 v7, v106 offset:6864
	s_waitcnt vmcnt(4)
	ds_write_b32 v7, v107 offset:7128
	s_waitcnt vmcnt(3)
	ds_write_b32 v7, v108 offset:7392
	s_waitcnt vmcnt(2)
	ds_write_b32 v7, v109 offset:7656
	s_waitcnt vmcnt(1)
	ds_write_b32 v7, v110 offset:7920
	s_waitcnt vmcnt(0)
	ds_write_b32 v7, v111 offset:8184
	s_branch .LBB0_7
